# phase_up Q epilogue RoPE blocks: all four cos/sin loads of a block issued together
# baseline (speedup 1.0000x reference)
.LBB0_967:
	s_and_b64 vcc, exec, s[0:1]
	s_cbranch_vccz .LBB0_916
	s_mul_hi_i32 s0, s12, 0x2aaaaaab
	s_lshr_b32 s1, s0, 31
	s_ashr_i32 s0, s0, 2
	s_add_i32 s0, s0, s1
	s_lshl_b32 s1, s0, 3
	s_and_b32 s4, s12, 7
	s_mulk_i32 s0, 0xffe8
	s_or_b32 s4, s1, s4
	s_add_i32 s0, s12, s0
	s_ashr_i32 s5, s4, 31
	s_ashr_i32 s0, s0, 3
	s_lshl_b64 s[6:7], s[4:5], 17
	v_readlane_b32 s14, v254, 29
	v_ashrrev_i32_e32 v1, 6, v139
	v_bfe_u32 v0, v139, 3, 3
	v_readlane_b32 s15, v254, 30
	s_add_u32 s6, s14, s6
	v_lshl_or_b32 v0, v1, 3, v0
	s_addc_u32 s7, s15, s7
	s_ashr_i32 s1, s0, 31
	v_lshlrev_b32_e32 v14, 10, v1
	v_lshrrev_b32_e32 v1, 1, v0
	s_lshl_b64 s[14:15], s[0:1], 17
	v_xor_b32_e32 v2, v1, v139
	v_add_u32_e32 v15, 32, v14
	v_ashrrev_i32_e32 v1, 31, v0
	s_add_u32 s14, s8, s14
	v_lshlrev_b64 v[6:7], 9, v[0:1]
	v_add_u32_e32 v10, 0x8000, v15
	s_mov_b64 s[16:17], 0x8000
	s_addc_u32 s15, s9, s15
	v_lshlrev_b32_e32 v2, 4, v2
	v_readfirstlane_b32 s19, v10
	v_lshl_add_u64 v[10:11], v[6:7], 0, s[16:17]
	v_and_b32_e32 v8, 0x70, v2
	v_mov_b32_e32 v9, v4
	v_lshl_add_u64 v[12:13], s[6:7], 0, v[10:11]
	v_lshl_add_u64 v[10:11], s[14:15], 0, v[10:11]
	v_lshl_add_u64 v[0:1], s[6:7], 0, v[6:7]
	v_readfirstlane_b32 s18, v15
	v_lshl_add_u64 v[136:137], v[10:11], 0, v[8:9]
	v_add_u32_e32 v10, 0xa000, v15
	s_mov_b64 s[16:17], 0x10000
	v_lshl_add_u64 v[0:1], v[0:1], 0, v[8:9]
	s_mov_b32 m0, s18
	v_lshl_add_u64 v[2:3], s[14:15], 0, v[6:7]
	v_add_u32_e32 v16, 0x2000, v15
	v_readfirstlane_b32 s21, v10
	v_lshl_add_u64 v[10:11], v[6:7], 0, s[16:17]
	global_load_lds_dwordx4 v[0:1], off
	v_lshl_add_u64 v[2:3], v[2:3], 0, v[8:9]
	s_mov_b32 m0, s19
	v_lshl_add_u64 v[134:135], v[12:13], 0, v[8:9]
	v_readfirstlane_b32 s20, v16
	v_lshl_add_u64 v[12:13], s[6:7], 0, v[10:11]
	v_lshl_add_u64 v[10:11], s[14:15], 0, v[10:11]
	s_mov_b64 s[16:17], 0x18000
	global_load_lds_dwordx4 v[2:3], off
	s_mov_b32 m0, s20
	v_add_u32_e32 v16, 0x4000, v15
	v_lshl_add_u64 v[146:147], v[10:11], 0, v[8:9]
	v_add_u32_e32 v10, 0xc000, v15
	v_lshl_add_u64 v[6:7], v[6:7], 0, s[16:17]
	global_load_lds_dwordx4 v[134:135], off
	s_mov_b32 m0, s21
	v_readfirstlane_b32 s22, v16
	v_readfirstlane_b32 s23, v10
	v_lshl_add_u64 v[10:11], s[6:7], 0, v[6:7]
	v_lshl_add_u64 v[6:7], s[14:15], 0, v[6:7]
	global_load_lds_dwordx4 v[136:137], off
	v_lshl_add_u64 v[144:145], v[12:13], 0, v[8:9]
	s_mov_b32 m0, s22
	v_add_u32_e32 v12, 0x6000, v15
	v_lshl_add_u64 v[150:151], v[6:7], 0, v[8:9]
	v_add_u32_e32 v6, 0xe000, v15
	global_load_lds_dwordx4 v[144:145], off
	s_mov_b32 m0, s23
	v_readfirstlane_b32 s35, v12
	v_readfirstlane_b32 s44, v6
	v_lshrrev_b32_e32 v6, 5, v139
	v_bfe_u32 v153, v139, 1, 3
	s_add_i32 s17, 32, 0x10000
	global_load_lds_dwordx4 v[146:147], off
	v_lshl_add_u64 v[148:149], v[10:11], 0, v[8:9]
	s_mov_b32 m0, s35
	v_bitop3_b32 v6, v6, v153, 1 bitop3:0x6c
	v_add_u32_e32 v8, s17, v14
	global_load_lds_dwordx4 v[148:149], off
	s_mov_b32 m0, s44
	v_lshlrev_b32_e32 v166, 4, v6
	v_lshlrev_b32_e32 v6, 7, v139
	v_readfirstlane_b32 s1, v8
	v_add_u32_e32 v9, 0x8000, v8
	global_load_lds_dwordx4 v[150:151], off
	v_and_b32_e32 v167, 0x6f80, v6
	v_lshl_add_u64 v[6:7], v[0:1], 0, s[54:55]
	s_mov_b32 m0, s1
	v_readfirstlane_b32 s5, v9
	v_add_u32_e32 v9, 0x2000, v8
	s_waitcnt vmcnt(0)
	s_waitcnt vmcnt(0) lgkmcnt(0)
	s_barrier
	global_load_lds_dwordx4 v[6:7], off
	v_lshl_add_u64 v[6:7], v[2:3], 0, s[54:55]
	s_mov_b32 m0, s5
	v_readfirstlane_b32 s6, v9
	v_add_u32_e32 v9, 0xa000, v8
	global_load_lds_dwordx4 v[6:7], off
	v_lshl_add_u64 v[6:7], v[134:135], 0, s[54:55]
	s_mov_b32 m0, s6
	v_readfirstlane_b32 s7, v9
	v_add_u32_e32 v9, 0x4000, v8
	global_load_lds_dwordx4 v[6:7], off
	v_lshl_add_u64 v[6:7], v[136:137], 0, s[54:55]
	s_mov_b32 m0, s7
	v_readfirstlane_b32 s13, v9
	v_add_u32_e32 v9, 0xc000, v8
	global_load_lds_dwordx4 v[6:7], off
	v_lshl_add_u64 v[6:7], v[144:145], 0, s[54:55]
	s_mov_b32 m0, s13
	v_readfirstlane_b32 s14, v9
	v_add_u32_e32 v9, 0x6000, v8
	global_load_lds_dwordx4 v[6:7], off
	v_lshl_add_u64 v[6:7], v[146:147], 0, s[54:55]
	s_mov_b32 m0, s14
	v_readfirstlane_b32 s15, v9
	v_add_u32_e32 v8, 0xe000, v8
	global_load_lds_dwordx4 v[6:7], off
	v_lshl_add_u64 v[6:7], v[148:149], 0, s[54:55]
	s_mov_b32 m0, s15
	v_readfirstlane_b32 s16, v8
	global_load_lds_dwordx4 v[6:7], off
	v_lshl_add_u64 v[6:7], v[150:151], 0, s[54:55]
	s_mov_b32 m0, s16
	v_add_u32_e32 v11, 32, v166
	global_load_lds_dwordx4 v[6:7], off
	v_add_u32_e32 v168, v11, v167
	v_and_b32_e32 v152, 31, v139
	v_lshrrev_b32_e32 v10, 1, v139
	ds_read_b128 v[6:9], v168 offset:32768
	ds_read_b128 v[14:17], v168 offset:36864
	s_mov_b32 s45, 0x1ffff80
	v_and_or_b32 v10, v10, s45, v152
	v_lshlrev_b32_e32 v169, 7, v10
	v_add_u32_e32 v170, v11, v169
	ds_read_b128 v[10:13], v170
	s_waitcnt lgkmcnt(0)
	v_mfma_f32_32x32x16_bf16 v[118:133], v[6:9], v[10:13], 0
	v_bfe_u32 v171, v139, 5, 1
	s_mov_b32 m0, s18
	s_add_i32 s18, 32, 0x18000
	v_add3_u32 v179, s18, v166, v167
	v_add3_u32 v166, s17, v166, v169
	v_mfma_f32_32x32x16_bf16 v[102:117], v[14:17], v[10:13], 0
	ds_read_b128 v[10:13], v170 offset:4096
	s_waitcnt lgkmcnt(0)
	v_mfma_f32_32x32x16_bf16 v[86:101], v[6:9], v[10:13], 0
	v_mfma_f32_32x32x16_bf16 v[70:85], v[14:17], v[10:13], 0
	ds_read_b128 v[10:13], v170 offset:8192
	s_waitcnt lgkmcnt(0)
	v_mfma_f32_32x32x16_bf16 v[54:69], v[6:9], v[10:13], 0
	v_mfma_f32_32x32x16_bf16 v[38:53], v[14:17], v[10:13], 0
	ds_read_b128 v[10:13], v170 offset:12288
	s_waitcnt lgkmcnt(0)
	v_mfma_f32_32x32x16_bf16 v[22:37], v[6:9], v[10:13], 0
	v_bitop3_b32 v6, v171, v153, 2 bitop3:0x36
	v_lshlrev_b32_e32 v172, 4, v6
	v_add_u32_e32 v158, 32, v172
	v_add_u32_e32 v173, v158, v167
	ds_read_b128 v[154:157], v173 offset:32768
	ds_read_b128 v[162:165], v173 offset:36864
	v_add_u32_e32 v174, v158, v169
	ds_read_b128 v[158:161], v174
	s_waitcnt lgkmcnt(0)
	v_mfma_f32_32x32x16_bf16 v[118:133], v[154:157], v[158:161], v[118:133]
	v_add3_u32 v180, s18, v172, v167
	v_add3_u32 v172, s17, v172, v169
	v_mfma_f32_32x32x16_bf16 v[102:117], v[162:165], v[158:161], v[102:117]
	ds_read_b128 v[158:161], v174 offset:4096
	s_waitcnt lgkmcnt(0)
	v_mfma_f32_32x32x16_bf16 v[86:101], v[154:157], v[158:161], v[86:101]
	v_mfma_f32_32x32x16_bf16 v[70:85], v[162:165], v[158:161], v[70:85]
	ds_read_b128 v[158:161], v174 offset:8192
	v_mfma_f32_32x32x16_bf16 v[6:21], v[14:17], v[10:13], 0
	s_waitcnt lgkmcnt(0)
	v_mfma_f32_32x32x16_bf16 v[54:69], v[154:157], v[158:161], v[54:69]
	v_mfma_f32_32x32x16_bf16 v[38:53], v[162:165], v[158:161], v[38:53]
	ds_read_b128 v[158:161], v174 offset:12288
	s_waitcnt lgkmcnt(0)
	v_mfma_f32_32x32x16_bf16 v[22:37], v[154:157], v[158:161], v[22:37]
	v_bitop3_b32 v154, v171, v153, 4 bitop3:0x36
	v_lshlrev_b32_e32 v175, 4, v154
	v_bitop3_b32 v153, v171, v153, 6 bitop3:0x36
	v_lshlrev_b32_e32 v153, 4, v153
	v_add3_u32 v181, s18, v175, v167
	v_mfma_f32_32x32x16_bf16 v[6:21], v[162:165], v[158:161], v[6:21]
	v_add_u32_e32 v158, 32, v175
	v_add_u32_e32 v176, v158, v167
	ds_read_b128 v[154:157], v176 offset:32768
	ds_read_b128 v[162:165], v176 offset:36864
	v_add_u32_e32 v177, v158, v169
	ds_read_b128 v[158:161], v177
	v_add3_u32 v175, s17, v175, v169
	s_waitcnt lgkmcnt(0)
	v_mfma_f32_32x32x16_bf16 v[118:133], v[154:157], v[158:161], v[118:133]
	v_mfma_f32_32x32x16_bf16 v[102:117], v[162:165], v[158:161], v[102:117]
	ds_read_b128 v[158:161], v177 offset:4096
	s_waitcnt lgkmcnt(0)
	v_mfma_f32_32x32x16_bf16 v[86:101], v[154:157], v[158:161], v[86:101]
	v_mfma_f32_32x32x16_bf16 v[70:85], v[162:165], v[158:161], v[70:85]
	ds_read_b128 v[158:161], v177 offset:8192
	s_waitcnt lgkmcnt(0)
	v_mfma_f32_32x32x16_bf16 v[54:69], v[154:157], v[158:161], v[54:69]
	v_mfma_f32_32x32x16_bf16 v[38:53], v[162:165], v[158:161], v[38:53]
	ds_read_b128 v[158:161], v177 offset:12288
	s_waitcnt lgkmcnt(0)
	v_mfma_f32_32x32x16_bf16 v[22:37], v[154:157], v[158:161], v[22:37]
	v_mfma_f32_32x32x16_bf16 v[6:21], v[162:165], v[158:161], v[6:21]
	v_add_u32_e32 v158, 32, v153
	v_add_u32_e32 v171, v158, v167
	ds_read_b128 v[154:157], v171 offset:32768
	ds_read_b128 v[162:165], v171 offset:36864
	v_add_u32_e32 v178, v158, v169
	ds_read_b128 v[158:161], v178
	v_add3_u32 v167, s18, v153, v167
	s_waitcnt lgkmcnt(0)
	v_mfma_f32_32x32x16_bf16 v[118:133], v[154:157], v[158:161], v[118:133]
	v_add3_u32 v153, s17, v153, v169
	v_mfma_f32_32x32x16_bf16 v[102:117], v[162:165], v[158:161], v[102:117]
	ds_read_b128 v[158:161], v178 offset:4096
	s_waitcnt lgkmcnt(0)
	v_mfma_f32_32x32x16_bf16 v[86:101], v[154:157], v[158:161], v[86:101]
	v_mfma_f32_32x32x16_bf16 v[70:85], v[162:165], v[158:161], v[70:85]
	ds_read_b128 v[158:161], v178 offset:8192
	s_waitcnt lgkmcnt(0)
	v_mfma_f32_32x32x16_bf16 v[54:69], v[154:157], v[158:161], v[54:69]
	v_mfma_f32_32x32x16_bf16 v[38:53], v[162:165], v[158:161], v[38:53]
	ds_read_b128 v[158:161], v178 offset:12288
	s_waitcnt vmcnt(0)
	s_waitcnt vmcnt(0) lgkmcnt(0)
	s_barrier
	v_mfma_f32_32x32x16_bf16 v[22:37], v[154:157], v[158:161], v[22:37]
	v_lshl_add_u64 v[154:155], v[0:1], 0, s[96:97]
	global_load_lds_dwordx4 v[154:155], off
	v_lshl_add_u64 v[154:155], v[2:3], 0, s[96:97]
	s_mov_b32 m0, s19
	s_mov_b64 s[18:19], 0x180
	global_load_lds_dwordx4 v[154:155], off
	v_lshl_add_u64 v[154:155], v[134:135], 0, s[96:97]
	s_mov_b32 m0, s20
	v_mfma_f32_32x32x16_bf16 v[6:21], v[162:165], v[158:161], v[6:21]
	global_load_lds_dwordx4 v[154:155], off
	v_lshl_add_u64 v[154:155], v[136:137], 0, s[96:97]
	s_mov_b32 m0, s21
	v_lshl_add_u64 v[0:1], v[0:1], 0, s[18:19]
	global_load_lds_dwordx4 v[154:155], off
	v_lshl_add_u64 v[154:155], v[144:145], 0, s[96:97]
	s_mov_b32 m0, s22
	s_nop 0
	global_load_lds_dwordx4 v[154:155], off
	v_lshl_add_u64 v[154:155], v[146:147], 0, s[96:97]
	s_mov_b32 m0, s23
	s_nop 0
	global_load_lds_dwordx4 v[154:155], off
	v_lshl_add_u64 v[154:155], v[148:149], 0, s[96:97]
	s_mov_b32 m0, s35
	s_nop 0
	global_load_lds_dwordx4 v[154:155], off
	v_lshl_add_u64 v[154:155], v[150:151], 0, s[96:97]
	s_mov_b32 m0, s44
	s_nop 0
	global_load_lds_dwordx4 v[154:155], off
	ds_read_b128 v[154:157], v179
	ds_read_b128 v[158:161], v166
	ds_read_b128 v[162:165], v179 offset:4096
	s_waitcnt lgkmcnt(0)
	v_mfma_f32_32x32x16_bf16 v[118:133], v[154:157], v[158:161], v[118:133]
	s_mov_b32 m0, s1
	s_movk_i32 s1, 0x9f
	v_mfma_f32_32x32x16_bf16 v[102:117], v[162:165], v[158:161], v[102:117]
	ds_read_b128 v[158:161], v166 offset:4096
	s_waitcnt lgkmcnt(0)
	v_mfma_f32_32x32x16_bf16 v[86:101], v[154:157], v[158:161], v[86:101]
	v_mfma_f32_32x32x16_bf16 v[70:85], v[162:165], v[158:161], v[70:85]
	ds_read_b128 v[158:161], v166 offset:8192
	s_waitcnt lgkmcnt(0)
	v_mfma_f32_32x32x16_bf16 v[54:69], v[154:157], v[158:161], v[54:69]
	v_mfma_f32_32x32x16_bf16 v[38:53], v[162:165], v[158:161], v[38:53]
	ds_read_b128 v[158:161], v166 offset:12288
	s_waitcnt lgkmcnt(0)
	v_mfma_f32_32x32x16_bf16 v[22:37], v[154:157], v[158:161], v[22:37]
	ds_read_b128 v[154:157], v180
	v_mfma_f32_32x32x16_bf16 v[6:21], v[162:165], v[158:161], v[6:21]
	ds_read_b128 v[162:165], v180 offset:4096
	ds_read_b128 v[158:161], v172
	s_waitcnt lgkmcnt(0)
	v_mfma_f32_32x32x16_bf16 v[118:133], v[154:157], v[158:161], v[118:133]
	v_mfma_f32_32x32x16_bf16 v[102:117], v[162:165], v[158:161], v[102:117]
	ds_read_b128 v[158:161], v172 offset:4096
	s_waitcnt lgkmcnt(0)
	v_mfma_f32_32x32x16_bf16 v[86:101], v[154:157], v[158:161], v[86:101]
	v_mfma_f32_32x32x16_bf16 v[70:85], v[162:165], v[158:161], v[70:85]
	ds_read_b128 v[158:161], v172 offset:8192
	s_waitcnt lgkmcnt(0)
	v_mfma_f32_32x32x16_bf16 v[54:69], v[154:157], v[158:161], v[54:69]
	v_mfma_f32_32x32x16_bf16 v[38:53], v[162:165], v[158:161], v[38:53]
	ds_read_b128 v[158:161], v172 offset:12288
	s_waitcnt lgkmcnt(0)
	v_mfma_f32_32x32x16_bf16 v[22:37], v[154:157], v[158:161], v[22:37]
	ds_read_b128 v[154:157], v181
	v_mfma_f32_32x32x16_bf16 v[6:21], v[162:165], v[158:161], v[6:21]
	ds_read_b128 v[162:165], v181 offset:4096
	ds_read_b128 v[158:161], v175
	s_waitcnt lgkmcnt(0)
	v_mfma_f32_32x32x16_bf16 v[118:133], v[154:157], v[158:161], v[118:133]
	v_mfma_f32_32x32x16_bf16 v[102:117], v[162:165], v[158:161], v[102:117]
	ds_read_b128 v[158:161], v175 offset:4096
	s_waitcnt lgkmcnt(0)
	v_mfma_f32_32x32x16_bf16 v[86:101], v[154:157], v[158:161], v[86:101]
	v_mfma_f32_32x32x16_bf16 v[70:85], v[162:165], v[158:161], v[70:85]
	ds_read_b128 v[158:161], v175 offset:8192
	s_waitcnt lgkmcnt(0)
	v_mfma_f32_32x32x16_bf16 v[54:69], v[154:157], v[158:161], v[54:69]
	v_mfma_f32_32x32x16_bf16 v[38:53], v[162:165], v[158:161], v[38:53]
	ds_read_b128 v[158:161], v175 offset:12288
	s_waitcnt lgkmcnt(0)
	v_mfma_f32_32x32x16_bf16 v[22:37], v[154:157], v[158:161], v[22:37]
	ds_read_b128 v[154:157], v167
	v_mfma_f32_32x32x16_bf16 v[6:21], v[162:165], v[158:161], v[6:21]
	ds_read_b128 v[162:165], v167 offset:4096
	ds_read_b128 v[158:161], v153
	s_waitcnt lgkmcnt(0)
	v_mfma_f32_32x32x16_bf16 v[118:133], v[154:157], v[158:161], v[118:133]
	v_mfma_f32_32x32x16_bf16 v[102:117], v[162:165], v[158:161], v[102:117]
	ds_read_b128 v[158:161], v153 offset:4096
	s_waitcnt lgkmcnt(0)
	v_mfma_f32_32x32x16_bf16 v[86:101], v[154:157], v[158:161], v[86:101]
	v_mfma_f32_32x32x16_bf16 v[70:85], v[162:165], v[158:161], v[70:85]
	ds_read_b128 v[158:161], v153 offset:8192
	s_waitcnt lgkmcnt(0)
	v_mfma_f32_32x32x16_bf16 v[54:69], v[154:157], v[158:161], v[54:69]
	v_mfma_f32_32x32x16_bf16 v[38:53], v[162:165], v[158:161], v[38:53]
	ds_read_b128 v[158:161], v153 offset:12288
	s_waitcnt vmcnt(0)
	s_waitcnt vmcnt(0) lgkmcnt(0)
	s_barrier
	global_load_lds_dwordx4 v[0:1], off
	v_lshl_add_u64 v[0:1], v[2:3], 0, s[18:19]
	s_mov_b32 m0, s5
	v_mfma_f32_32x32x16_bf16 v[22:37], v[154:157], v[158:161], v[22:37]
	global_load_lds_dwordx4 v[0:1], off
	v_lshl_add_u64 v[0:1], v[134:135], 0, s[18:19]
	s_mov_b32 m0, s6
	s_nop 0
	global_load_lds_dwordx4 v[0:1], off
	v_lshl_add_u64 v[0:1], v[136:137], 0, s[18:19]
	s_mov_b32 m0, s7
	v_mfma_f32_32x32x16_bf16 v[6:21], v[162:165], v[158:161], v[6:21]
	global_load_lds_dwordx4 v[0:1], off
	v_lshl_add_u64 v[0:1], v[144:145], 0, s[18:19]
	s_mov_b32 m0, s13
	s_nop 0
	global_load_lds_dwordx4 v[0:1], off
	v_lshl_add_u64 v[0:1], v[146:147], 0, s[18:19]
	s_mov_b32 m0, s14
	s_nop 0
	global_load_lds_dwordx4 v[0:1], off
	v_lshl_add_u64 v[0:1], v[148:149], 0, s[18:19]
	s_mov_b32 m0, s15
	s_nop 0
	global_load_lds_dwordx4 v[0:1], off
	v_lshl_add_u64 v[0:1], v[150:151], 0, s[18:19]
	s_mov_b32 m0, s16
	s_nop 0
	global_load_lds_dwordx4 v[0:1], off
	ds_read_b128 v[0:3], v168 offset:32768
	ds_read_b128 v[134:137], v170
	ds_read_b128 v[144:147], v168 offset:36864
	s_waitcnt lgkmcnt(0)
	v_mfma_f32_32x32x16_bf16 v[118:133], v[0:3], v[134:137], v[118:133]
	v_mfma_f32_32x32x16_bf16 v[102:117], v[144:147], v[134:137], v[102:117]
	ds_read_b128 v[134:137], v170 offset:4096
	s_waitcnt lgkmcnt(0)
	v_mfma_f32_32x32x16_bf16 v[86:101], v[0:3], v[134:137], v[86:101]
	v_mfma_f32_32x32x16_bf16 v[70:85], v[144:147], v[134:137], v[70:85]
	ds_read_b128 v[134:137], v170 offset:8192
	s_waitcnt lgkmcnt(0)
	v_mfma_f32_32x32x16_bf16 v[54:69], v[0:3], v[134:137], v[54:69]
	v_mfma_f32_32x32x16_bf16 v[38:53], v[144:147], v[134:137], v[38:53]
	ds_read_b128 v[134:137], v170 offset:12288
	s_waitcnt lgkmcnt(0)
	v_mfma_f32_32x32x16_bf16 v[22:37], v[0:3], v[134:137], v[22:37]
	v_mfma_f32_32x32x16_bf16 v[6:21], v[144:147], v[134:137], v[6:21]
	ds_read_b128 v[0:3], v173 offset:32768
	ds_read_b128 v[134:137], v174
	ds_read_b128 v[144:147], v173 offset:36864
	s_waitcnt lgkmcnt(0)
	v_mfma_f32_32x32x16_bf16 v[118:133], v[0:3], v[134:137], v[118:133]
	v_mfma_f32_32x32x16_bf16 v[102:117], v[144:147], v[134:137], v[102:117]
	ds_read_b128 v[134:137], v174 offset:4096
	s_waitcnt lgkmcnt(0)
	v_mfma_f32_32x32x16_bf16 v[86:101], v[0:3], v[134:137], v[86:101]
	v_mfma_f32_32x32x16_bf16 v[70:85], v[144:147], v[134:137], v[70:85]
	ds_read_b128 v[134:137], v174 offset:8192
	s_waitcnt lgkmcnt(0)
	v_mfma_f32_32x32x16_bf16 v[54:69], v[0:3], v[134:137], v[54:69]
	v_mfma_f32_32x32x16_bf16 v[38:53], v[144:147], v[134:137], v[38:53]
	ds_read_b128 v[134:137], v174 offset:12288
	s_waitcnt lgkmcnt(0)
	v_mfma_f32_32x32x16_bf16 v[22:37], v[0:3], v[134:137], v[22:37]
	v_mfma_f32_32x32x16_bf16 v[6:21], v[144:147], v[134:137], v[6:21]
	ds_read_b128 v[0:3], v176 offset:32768
	ds_read_b128 v[134:137], v177
	ds_read_b128 v[144:147], v176 offset:36864
	s_waitcnt lgkmcnt(0)
	v_mfma_f32_32x32x16_bf16 v[118:133], v[0:3], v[134:137], v[118:133]
	v_mfma_f32_32x32x16_bf16 v[102:117], v[144:147], v[134:137], v[102:117]
	ds_read_b128 v[134:137], v177 offset:4096
	s_waitcnt lgkmcnt(0)
	v_mfma_f32_32x32x16_bf16 v[86:101], v[0:3], v[134:137], v[86:101]
	v_mfma_f32_32x32x16_bf16 v[70:85], v[144:147], v[134:137], v[70:85]
	ds_read_b128 v[134:137], v177 offset:8192
	s_waitcnt lgkmcnt(0)
	v_mfma_f32_32x32x16_bf16 v[54:69], v[0:3], v[134:137], v[54:69]
	v_mfma_f32_32x32x16_bf16 v[38:53], v[144:147], v[134:137], v[38:53]
	ds_read_b128 v[134:137], v177 offset:12288
	s_waitcnt lgkmcnt(0)
	v_mfma_f32_32x32x16_bf16 v[22:37], v[0:3], v[134:137], v[22:37]
	v_mfma_f32_32x32x16_bf16 v[6:21], v[144:147], v[134:137], v[6:21]
	ds_read_b128 v[0:3], v171 offset:32768
	ds_read_b128 v[134:137], v178
	ds_read_b128 v[144:147], v171 offset:36864
	s_waitcnt lgkmcnt(0)
	v_mfma_f32_32x32x16_bf16 v[118:133], v[0:3], v[134:137], v[118:133]
	v_mfma_f32_32x32x16_bf16 v[102:117], v[144:147], v[134:137], v[102:117]
	ds_read_b128 v[134:137], v178 offset:4096
	s_waitcnt lgkmcnt(0)
	v_mfma_f32_32x32x16_bf16 v[86:101], v[0:3], v[134:137], v[86:101]
	v_mfma_f32_32x32x16_bf16 v[70:85], v[144:147], v[134:137], v[70:85]
	ds_read_b128 v[134:137], v178 offset:8192
	s_waitcnt lgkmcnt(0)
	v_mfma_f32_32x32x16_bf16 v[54:69], v[0:3], v[134:137], v[54:69]
	v_mfma_f32_32x32x16_bf16 v[38:53], v[144:147], v[134:137], v[38:53]
	ds_read_b128 v[134:137], v178 offset:12288
	s_waitcnt vmcnt(0)
	s_waitcnt vmcnt(0) lgkmcnt(0)
	s_barrier
	v_mfma_f32_32x32x16_bf16 v[22:37], v[0:3], v[134:137], v[22:37]
	v_mfma_f32_32x32x16_bf16 v[6:21], v[144:147], v[134:137], v[6:21]
	ds_read_b128 v[0:3], v179
	ds_read_b128 v[134:137], v166
	ds_read_b128 v[144:147], v179 offset:4096
	s_waitcnt lgkmcnt(1)
	v_mfma_f32_32x32x16_bf16 v[118:133], v[0:3], v[134:137], v[118:133]
	s_waitcnt lgkmcnt(0)
	v_mfma_f32_32x32x16_bf16 v[102:117], v[144:147], v[134:137], v[102:117]
	ds_read_b128 v[134:137], v166 offset:4096
	s_waitcnt lgkmcnt(0)
	v_mfma_f32_32x32x16_bf16 v[86:101], v[0:3], v[134:137], v[86:101]
	v_mfma_f32_32x32x16_bf16 v[70:85], v[144:147], v[134:137], v[70:85]
	ds_read_b128 v[134:137], v166 offset:8192
	s_waitcnt lgkmcnt(0)
	v_mfma_f32_32x32x16_bf16 v[54:69], v[0:3], v[134:137], v[54:69]
	v_mfma_f32_32x32x16_bf16 v[38:53], v[144:147], v[134:137], v[38:53]
	ds_read_b128 v[134:137], v166 offset:12288
	s_waitcnt lgkmcnt(0)
	v_mfma_f32_32x32x16_bf16 v[22:37], v[0:3], v[134:137], v[22:37]
	v_mfma_f32_32x32x16_bf16 v[6:21], v[144:147], v[134:137], v[6:21]
	ds_read_b128 v[0:3], v180
	ds_read_b128 v[134:137], v172
	ds_read_b128 v[144:147], v180 offset:4096
	s_waitcnt lgkmcnt(1)
	v_mfma_f32_32x32x16_bf16 v[118:133], v[0:3], v[134:137], v[118:133]
	s_waitcnt lgkmcnt(0)
	v_mfma_f32_32x32x16_bf16 v[102:117], v[144:147], v[134:137], v[102:117]
	ds_read_b128 v[134:137], v172 offset:4096
	s_waitcnt lgkmcnt(0)
	v_mfma_f32_32x32x16_bf16 v[86:101], v[0:3], v[134:137], v[86:101]
	v_mfma_f32_32x32x16_bf16 v[70:85], v[144:147], v[134:137], v[70:85]
	ds_read_b128 v[134:137], v172 offset:8192
	s_waitcnt lgkmcnt(0)
	v_mfma_f32_32x32x16_bf16 v[54:69], v[0:3], v[134:137], v[54:69]
	v_mfma_f32_32x32x16_bf16 v[38:53], v[144:147], v[134:137], v[38:53]
	ds_read_b128 v[134:137], v172 offset:12288
	s_waitcnt lgkmcnt(0)
	v_mfma_f32_32x32x16_bf16 v[22:37], v[0:3], v[134:137], v[22:37]
	v_mfma_f32_32x32x16_bf16 v[6:21], v[144:147], v[134:137], v[6:21]
	ds_read_b128 v[0:3], v181
	ds_read_b128 v[134:137], v175
	ds_read_b128 v[144:147], v181 offset:4096
	s_waitcnt lgkmcnt(1)
	v_mfma_f32_32x32x16_bf16 v[118:133], v[0:3], v[134:137], v[118:133]
	s_waitcnt lgkmcnt(0)
	v_mfma_f32_32x32x16_bf16 v[102:117], v[144:147], v[134:137], v[102:117]
	ds_read_b128 v[134:137], v175 offset:4096
	s_waitcnt lgkmcnt(0)
	v_mfma_f32_32x32x16_bf16 v[86:101], v[0:3], v[134:137], v[86:101]
	v_mfma_f32_32x32x16_bf16 v[70:85], v[144:147], v[134:137], v[70:85]
	ds_read_b128 v[134:137], v175 offset:8192
	s_waitcnt lgkmcnt(0)
	v_mfma_f32_32x32x16_bf16 v[54:69], v[0:3], v[134:137], v[54:69]
	v_mfma_f32_32x32x16_bf16 v[38:53], v[144:147], v[134:137], v[38:53]
	ds_read_b128 v[134:137], v175 offset:12288
	s_waitcnt lgkmcnt(0)
	v_mfma_f32_32x32x16_bf16 v[22:37], v[0:3], v[134:137], v[22:37]
	v_mfma_f32_32x32x16_bf16 v[6:21], v[144:147], v[134:137], v[6:21]
	ds_read_b128 v[0:3], v167
	ds_read_b128 v[134:137], v153
	ds_read_b128 v[154:157], v167 offset:4096
	ds_read_b128 v[158:161], v153 offset:12288
	v_ashrrev_i32_e32 v144, 1, v139
	v_mov_b64_e32 v[146:147], 0xb152000
	s_waitcnt lgkmcnt(2)
	v_mfma_f32_32x32x16_bf16 v[118:133], v[0:3], v[134:137], v[118:133]
	s_waitcnt lgkmcnt(1)
	v_mfma_f32_32x32x16_bf16 v[102:117], v[154:157], v[134:137], v[102:117]
	ds_read_b128 v[134:137], v153 offset:4096
	s_waitcnt lgkmcnt(0)
	v_mfma_f32_32x32x16_bf16 v[86:101], v[0:3], v[134:137], v[86:101]
	v_mfma_f32_32x32x16_bf16 v[70:85], v[154:157], v[134:137], v[70:85]
	ds_read_b128 v[134:137], v153 offset:8192
	s_waitcnt vmcnt(0)
	s_waitcnt lgkmcnt(0)
	s_barrier
	v_mfma_f32_32x32x16_bf16 v[54:69], v[0:3], v[134:137], v[54:69]
	v_mfma_f32_32x32x16_bf16 v[38:53], v[154:157], v[134:137], v[38:53]
	v_and_b32_e32 v134, 0xffffff80, v144
	v_or_b32_e32 v135, v134, v152
	v_lshl_add_u32 v149, s4, 8, v135
	v_bitop3_b32 v136, v134, s1, v152 bitop3:0xc8
	v_ashrrev_i32_e32 v134, 5, v149
	v_and_b32_e32 v148, -8, v134
	v_cmp_lt_i32_e64 s[6:7], s89, v149
	v_mfma_f32_32x32x16_bf16 v[22:37], v[0:3], v[158:161], v[22:37]
	v_add_u32_e32 v0, 0xffffe000, v149
	v_lshrrev_b32_e32 v0, 9, v0
	v_mov_b64_e32 v[2:3], 8
	v_and_b32_e32 v137, 0xf9f, v149
	v_and_b32_e32 v150, 0x7ffff8, v0
	v_mov_b32_e32 v3, v148
	v_mov_b32_e32 v144, v136
	v_mfma_f32_32x32x16_bf16 v[6:21], v[154:157], v[158:161], v[6:21]
	s_and_saveexec_b64 s[4:5], s[6:7]
	v_mov_b64_e32 v[2:3], 12
	v_mov_b64_e32 v[146:147], 0xbd52000
	v_mov_b32_e32 v3, v150
	v_mov_b32_e32 v144, v137
	s_or_b64 exec, exec, s[4:5]
	v_and_b32_e32 v1, 0xc0, v139
	v_lshrrev_b32_e32 v0, 3, v139
	v_lshl_or_b32 v151, s0, 8, v1
	s_mov_b32 s0, 0x2aaaaaab
	v_and_b32_e32 v152, 4, v0
	v_mul_hi_i32 v0, v151, s0
	v_lshrrev_b32_e32 v1, 31, v0
	v_ashrrev_i32_e32 v0, 4, v0
	v_add_u32_e32 v139, v0, v1
	s_movk_i32 s0, 0x60
	v_mul_lo_u32 v0, v139, s0
	v_sub_u32_e32 v134, v151, v0
	v_cmp_eq_u32_e32 vcc, 64, v134
	s_and_b64 s[4:5], s[6:7], vcc
	v_lshlrev_b32_e32 v0, 2, v152
	s_and_saveexec_b64 s[0:1], s[4:5]
	s_cbranch_execz .LBB0_972
	v_readlane_b32 s4, v253, 31
	v_lshlrev_b32_e32 v154, 7, v144
	v_mov_b32_e32 v155, v4
	v_readlane_b32 s5, v253, 32
	v_mov_b32_e32 v1, v4
	s_nop 0
	v_lshl_add_u64 v[156:157], s[4:5], 0, v[154:155]
	v_readlane_b32 s4, v254, 47
	v_readlane_b32 s5, v254, 48
	v_lshl_add_u64 v[162:163], v[156:157], 0, v[0:1]
	s_nop 0
	v_lshl_add_u64 v[154:155], s[4:5], 0, v[154:155]
	v_lshl_add_u64 v[164:165], v[154:155], 0, v[0:1]
	global_load_dwordx4 v[154:157], v[162:163], off
	global_load_dwordx4 v[158:161], v[164:165], off
	global_load_dwordx4 v[194:197], v[162:163], off offset:64
	global_load_dwordx4 v[198:201], v[164:165], off offset:64
	s_waitcnt vmcnt(2)
	v_pk_mul_f32 v[166:167], v[122:123], v[158:159]
	s_nop 0
	v_pk_fma_f32 v[166:167], v[118:119], v[154:155], v[166:167] neg_lo:[0,0,1] neg_hi:[0,0,1]
	v_pk_mul_f32 v[118:119], v[118:119], v[158:159]
	s_nop 0
	v_pk_fma_f32 v[122:123], v[122:123], v[154:155], v[118:119]
	v_pk_mul_f32 v[118:119], v[124:125], v[160:161]
	s_nop 0
	v_pk_fma_f32 v[158:159], v[120:121], v[156:157], v[118:119] neg_lo:[0,0,1] neg_hi:[0,0,1]
	v_pk_mul_f32 v[118:119], v[120:121], v[160:161]
	s_nop 0
	v_pk_fma_f32 v[124:125], v[124:125], v[156:157], v[118:119]
	s_waitcnt vmcnt(0)
	v_pk_mul_f32 v[160:161], v[130:131], v[198:199]
	s_nop 0
	v_pk_fma_f32 v[160:161], v[126:127], v[194:195], v[160:161] neg_lo:[0,0,1] neg_hi:[0,0,1]
	v_pk_mul_f32 v[126:127], v[126:127], v[198:199]
	s_nop 0
	v_pk_fma_f32 v[130:131], v[130:131], v[194:195], v[126:127]
	v_pk_mul_f32 v[118:119], v[132:133], v[200:201]
	v_mov_b32_e32 v126, v160
	v_pk_fma_f32 v[154:155], v[128:129], v[196:197], v[118:119] neg_lo:[0,0,1] neg_hi:[0,0,1]
	v_pk_mul_f32 v[118:119], v[128:129], v[200:201]
	v_mov_b32_e32 v127, v161
	v_pk_fma_f32 v[132:133], v[132:133], v[196:197], v[118:119]
	v_mov_b32_e32 v118, v166
	v_mov_b32_e32 v119, v167
	v_mov_b32_e32 v120, v158
	v_mov_b32_e32 v121, v159
	v_mov_b32_e32 v128, v154
	v_mov_b32_e32 v129, v155
.LBB0_972:
	s_or_b64 exec, exec, s[0:1]
	v_add_u32_e32 v154, v3, v139
	v_ashrrev_i32_e32 v155, 31, v154
	v_lshlrev_b64 v[2:3], v2, v[154:155]
	v_mov_b32_e32 v145, v4
	v_lshl_add_u64 v[146:147], s[26:27], 0, v[146:147]
	v_lshl_add_u64 v[2:3], v[2:3], 0, v[144:145]
	v_mad_u64_u32 v[144:145], s[0:1], v2, s50, v[146:147]
	v_mad_i32_i24 v145, v3, s50, v145
	v_ashrrev_i32_e32 v135, 31, v134
	v_lshl_add_u64 v[144:145], v[134:135], 1, v[144:145]
	v_lshlrev_b32_e32 v2, 1, v152
	v_mov_b32_e32 v3, v4
	v_pk_mul_f32 v[118:119], v[118:119], s[64:65] op_sel_hi:[1,0]
	v_pk_mul_f32 v[120:121], v[120:121], s[64:65] op_sel_hi:[1,0]
	v_lshl_add_u64 v[144:145], v[144:145], 0, v[2:3]
	v_cvt_pk_bf16_f32 v118, v118, v119
	v_cvt_pk_bf16_f32 v119, v120, v121
	s_nop 0
	v_readfirstlane_b32 s70, v144
	v_readfirstlane_b32 s71, v145
	ds_write_b64 v182, v[118:119]
	v_pk_mul_f32 v[118:119], v[122:123], s[64:65] op_sel_hi:[1,0]
	v_pk_mul_f32 v[120:121], v[124:125], s[64:65] op_sel_hi:[1,0]
	v_cvt_pk_bf16_f32 v118, v118, v119
	v_cvt_pk_bf16_f32 v119, v120, v121
	ds_write_b64 v182, v[118:119] offset:16
	v_pk_mul_f32 v[118:119], v[126:127], s[64:65] op_sel_hi:[1,0]
	v_pk_mul_f32 v[120:121], v[128:129], s[64:65] op_sel_hi:[1,0]
	v_cvt_pk_bf16_f32 v118, v118, v119
	v_cvt_pk_bf16_f32 v119, v120, v121
	ds_write_b64 v182, v[118:119] offset:32
	v_pk_mul_f32 v[118:119], v[130:131], s[64:65] op_sel_hi:[1,0]
	v_pk_mul_f32 v[120:121], v[132:133], s[64:65] op_sel_hi:[1,0]
	v_cvt_pk_bf16_f32 v118, v118, v119
	v_cvt_pk_bf16_f32 v119, v120, v121
	v_mov_b64_e32 v[122:123], 0xb152000
	v_mov_b64_e32 v[120:121], 8
	v_mov_b32_e32 v3, v148
	ds_write_b64 v182, v[118:119] offset:48
	ds_read_b128 v[186:189], v183
	ds_read_b128 v[190:193], v183 offset:1280
	s_waitcnt lgkmcnt(1)
	global_store_dwordx4 v184, v[186:189], s[70:71]
	s_waitcnt lgkmcnt(0)
	global_store_dwordx4 v184, v[190:193], s[70:71] offset:3072
	s_and_saveexec_b64 s[0:1], s[6:7]
	v_mov_b64_e32 v[122:123], 0xbd52000
	v_mov_b64_e32 v[120:121], 12
	v_mov_b32_e32 v3, v150
	v_mov_b32_e32 v136, v137
	s_or_b64 exec, exec, s[0:1]
	v_or_b32_e32 v1, 32, v151
	s_mov_b32 s0, 0x2aaaaaab
	v_mul_hi_i32 v118, v1, s0
	v_lshrrev_b32_e32 v119, 31, v118
	v_ashrrev_i32_e32 v118, 4, v118
	v_add_u32_e32 v121, v118, v119
	s_movk_i32 s0, 0x60
	v_mul_lo_u32 v118, v121, s0
	v_sub_u32_e32 v118, v1, v118
	v_cmp_eq_u32_e64 s[4:5], 64, v118
	s_and_b64 s[6:7], s[6:7], s[4:5]
	s_and_saveexec_b64 s[0:1], s[6:7]
	s_cbranch_execz .LBB0_976
	v_readlane_b32 s6, v253, 31
	v_lshlrev_b32_e32 v124, 7, v136
	v_mov_b32_e32 v125, v4
	v_readlane_b32 s7, v253, 32
	v_mov_b32_e32 v1, v4
	s_nop 0
	v_lshl_add_u64 v[126:127], s[6:7], 0, v[124:125]
	v_readlane_b32 s6, v254, 47
	v_readlane_b32 s7, v254, 48
	v_lshl_add_u64 v[132:133], v[126:127], 0, v[0:1]
	s_nop 0
	v_lshl_add_u64 v[124:125], s[6:7], 0, v[124:125]
	v_lshl_add_u64 v[144:145], v[124:125], 0, v[0:1]
	global_load_dwordx4 v[124:127], v[132:133], off
	global_load_dwordx4 v[128:131], v[144:145], off
	global_load_dwordx4 v[194:197], v[132:133], off offset:64
	global_load_dwordx4 v[198:201], v[144:145], off offset:64
	s_waitcnt vmcnt(2)
	v_pk_mul_f32 v[146:147], v[106:107], v[128:129]
	s_nop 0
	v_pk_fma_f32 v[146:147], v[102:103], v[124:125], v[146:147] neg_lo:[0,0,1] neg_hi:[0,0,1]
	v_pk_mul_f32 v[102:103], v[102:103], v[128:129]
	s_nop 0
	v_pk_fma_f32 v[106:107], v[106:107], v[124:125], v[102:103]
	v_pk_mul_f32 v[102:103], v[108:109], v[130:131]
	s_nop 0
	v_pk_fma_f32 v[128:129], v[104:105], v[126:127], v[102:103] neg_lo:[0,0,1] neg_hi:[0,0,1]
	v_pk_mul_f32 v[102:103], v[104:105], v[130:131]
	s_nop 0
	v_pk_fma_f32 v[108:109], v[108:109], v[126:127], v[102:103]
	s_waitcnt vmcnt(0)
	v_pk_mul_f32 v[130:131], v[114:115], v[198:199]
	s_nop 0
	v_pk_fma_f32 v[130:131], v[110:111], v[194:195], v[130:131] neg_lo:[0,0,1] neg_hi:[0,0,1]
	v_pk_mul_f32 v[110:111], v[110:111], v[198:199]
	s_nop 0
	v_pk_fma_f32 v[114:115], v[114:115], v[194:195], v[110:111]
	v_pk_mul_f32 v[102:103], v[116:117], v[200:201]
	v_mov_b32_e32 v110, v130
	v_pk_fma_f32 v[124:125], v[112:113], v[196:197], v[102:103] neg_lo:[0,0,1] neg_hi:[0,0,1]
	v_pk_mul_f32 v[102:103], v[112:113], v[200:201]
	v_mov_b32_e32 v111, v131
	v_pk_fma_f32 v[116:117], v[116:117], v[196:197], v[102:103]
	v_mov_b32_e32 v102, v146
	v_mov_b32_e32 v103, v147
	v_mov_b32_e32 v104, v128
	v_mov_b32_e32 v105, v129
	v_mov_b32_e32 v112, v124
	v_mov_b32_e32 v113, v125
.LBB0_976:
	s_or_b64 exec, exec, s[0:1]
	v_add_u32_e32 v124, v3, v121
	v_ashrrev_i32_e32 v125, 31, v124
	v_lshlrev_b64 v[124:125], v120, v[124:125]
	v_mov_b32_e32 v137, v4
	v_lshl_add_u64 v[122:123], s[26:27], 0, v[122:123]
	v_lshl_add_u64 v[124:125], v[124:125], 0, v[136:137]
	v_mad_u64_u32 v[122:123], s[0:1], v124, s50, v[122:123]
	v_mad_i32_i24 v123, v125, s50, v123
	v_ashrrev_i32_e32 v119, 31, v118
	v_lshl_add_u64 v[122:123], v[118:119], 1, v[122:123]
	v_mov_b32_e32 v3, v4
	v_pk_mul_f32 v[102:103], v[102:103], s[64:65] op_sel_hi:[1,0]
	v_pk_mul_f32 v[104:105], v[104:105], s[64:65] op_sel_hi:[1,0]
	v_lshl_add_u64 v[122:123], v[122:123], 0, v[2:3]
	v_cvt_pk_bf16_f32 v102, v102, v103
	v_cvt_pk_bf16_f32 v103, v104, v105
	s_nop 0
	v_readfirstlane_b32 s70, v122
	v_readfirstlane_b32 s71, v123
	ds_write_b64 v182, v[102:103]
	v_pk_mul_f32 v[102:103], v[106:107], s[64:65] op_sel_hi:[1,0]
	v_pk_mul_f32 v[104:105], v[108:109], s[64:65] op_sel_hi:[1,0]
	v_cvt_pk_bf16_f32 v102, v102, v103
	v_cvt_pk_bf16_f32 v103, v104, v105
	ds_write_b64 v182, v[102:103] offset:16
	v_pk_mul_f32 v[102:103], v[110:111], s[64:65] op_sel_hi:[1,0]
	v_pk_mul_f32 v[104:105], v[112:113], s[64:65] op_sel_hi:[1,0]
	v_cvt_pk_bf16_f32 v102, v102, v103
	v_cvt_pk_bf16_f32 v103, v104, v105
	ds_write_b64 v182, v[102:103] offset:32
	v_pk_mul_f32 v[102:103], v[114:115], s[64:65] op_sel_hi:[1,0]
	v_pk_mul_f32 v[104:105], v[116:117], s[64:65] op_sel_hi:[1,0]
	v_or_b32_e32 v1, 32, v149
	v_cvt_pk_bf16_f32 v102, v102, v103
	v_cvt_pk_bf16_f32 v103, v104, v105
	v_cmp_lt_i32_e64 s[6:7], s89, v1
	s_movk_i32 s0, 0xbf
	v_add_u32_e32 v1, 0xffffe020, v149
	ds_write_b64 v182, v[102:103] offset:48
	ds_read_b128 v[186:189], v183
	ds_read_b128 v[190:193], v183 offset:1280
	s_waitcnt lgkmcnt(1)
	global_store_dwordx4 v184, v[186:189], s[70:71]
	s_waitcnt lgkmcnt(0)
	global_store_dwordx4 v184, v[190:193], s[70:71] offset:3072
	v_bitop3_b32 v102, v149, s0, 32 bitop3:0xc8
	s_movk_i32 s0, 0xfbf
	v_lshrrev_b32_e32 v1, 9, v1
	v_bitop3_b32 v103, v149, s0, 32 bitop3:0xc8
	v_and_b32_e32 v110, 0x7ffff8, v1
	v_mov_b64_e32 v[108:109], 0xb152000
	v_mov_b64_e32 v[104:105], 8
	v_mov_b32_e32 v3, v148
	v_mov_b32_e32 v106, v102
	s_and_saveexec_b64 s[0:1], s[6:7]
	v_mov_b64_e32 v[108:109], 0xbd52000
	v_mov_b64_e32 v[104:105], 12
	v_mov_b32_e32 v3, v110
	v_mov_b32_e32 v106, v103
	s_or_b64 exec, exec, s[0:1]
	s_and_b64 s[14:15], s[6:7], vcc
	s_and_saveexec_b64 s[0:1], s[14:15]
	s_cbranch_execz .LBB0_980
	v_readlane_b32 s14, v253, 31
	v_lshlrev_b32_e32 v112, 7, v106
	v_mov_b32_e32 v113, v4
	v_readlane_b32 s15, v253, 32
	v_mov_b32_e32 v1, v4
	s_nop 0
	v_lshl_add_u64 v[114:115], s[14:15], 0, v[112:113]
	v_readlane_b32 s14, v254, 47
	v_readlane_b32 s15, v254, 48
	v_lshl_add_u64 v[116:117], v[114:115], 0, v[0:1]
	s_nop 0
	v_lshl_add_u64 v[112:113], s[14:15], 0, v[112:113]
	v_lshl_add_u64 v[126:127], v[112:113], 0, v[0:1]
	global_load_dwordx4 v[112:115], v[116:117], off
	global_load_dwordx4 v[122:125], v[126:127], off
	global_load_dwordx4 v[194:197], v[116:117], off offset:64
	global_load_dwordx4 v[198:201], v[126:127], off offset:64
	s_waitcnt vmcnt(2)
	v_pk_mul_f32 v[128:129], v[90:91], v[122:123]
	s_nop 0
	v_pk_fma_f32 v[128:129], v[86:87], v[112:113], v[128:129] neg_lo:[0,0,1] neg_hi:[0,0,1]
	v_pk_mul_f32 v[86:87], v[86:87], v[122:123]
	s_nop 0
	v_pk_fma_f32 v[90:91], v[90:91], v[112:113], v[86:87]
	v_pk_mul_f32 v[86:87], v[92:93], v[124:125]
	s_nop 0
	v_pk_fma_f32 v[122:123], v[88:89], v[114:115], v[86:87] neg_lo:[0,0,1] neg_hi:[0,0,1]
	v_pk_mul_f32 v[86:87], v[88:89], v[124:125]
	s_nop 0
	v_pk_fma_f32 v[92:93], v[92:93], v[114:115], v[86:87]
	s_waitcnt vmcnt(0)
	v_pk_mul_f32 v[116:117], v[98:99], v[198:199]
	s_nop 0
	v_pk_fma_f32 v[116:117], v[94:95], v[194:195], v[116:117] neg_lo:[0,0,1] neg_hi:[0,0,1]
	v_pk_mul_f32 v[94:95], v[94:95], v[198:199]
	s_nop 0
	v_pk_fma_f32 v[98:99], v[98:99], v[194:195], v[94:95]
	v_pk_mul_f32 v[86:87], v[100:101], v[200:201]
	v_mov_b32_e32 v94, v116
	v_pk_fma_f32 v[112:113], v[96:97], v[196:197], v[86:87] neg_lo:[0,0,1] neg_hi:[0,0,1]
	v_pk_mul_f32 v[86:87], v[96:97], v[200:201]
	v_mov_b32_e32 v95, v117
	v_pk_fma_f32 v[100:101], v[100:101], v[196:197], v[86:87]
	v_mov_b32_e32 v86, v128
	v_mov_b32_e32 v87, v129
	v_mov_b32_e32 v88, v122
	v_mov_b32_e32 v89, v123
	v_mov_b32_e32 v96, v112
	v_mov_b32_e32 v97, v113
.LBB0_980:
	s_or_b64 exec, exec, s[0:1]
	v_add_u32_e32 v112, v3, v139
	v_ashrrev_i32_e32 v113, 31, v112
	v_lshlrev_b64 v[104:105], v104, v[112:113]
	v_mov_b32_e32 v107, v4
	v_lshl_add_u64 v[108:109], s[26:27], 0, v[108:109]
	v_lshl_add_u64 v[104:105], v[104:105], 0, v[106:107]
	v_mad_u64_u32 v[106:107], s[0:1], v104, s50, v[108:109]
	v_mad_i32_i24 v107, v105, s50, v107
	v_lshl_add_u64 v[104:105], v[134:135], 1, v[106:107]
	v_mov_b32_e32 v3, v4
	v_pk_mul_f32 v[86:87], v[86:87], s[64:65] op_sel_hi:[1,0]
	v_pk_mul_f32 v[88:89], v[88:89], s[64:65] op_sel_hi:[1,0]
	v_lshl_add_u64 v[104:105], v[104:105], 0, v[2:3]
	v_cvt_pk_bf16_f32 v86, v86, v87
	v_cvt_pk_bf16_f32 v87, v88, v89
	s_nop 0
	v_readfirstlane_b32 s70, v104
	v_readfirstlane_b32 s71, v105
	ds_write_b64 v182, v[86:87]
	v_pk_mul_f32 v[86:87], v[90:91], s[64:65] op_sel_hi:[1,0]
	v_pk_mul_f32 v[88:89], v[92:93], s[64:65] op_sel_hi:[1,0]
	v_cvt_pk_bf16_f32 v86, v86, v87
	v_cvt_pk_bf16_f32 v87, v88, v89
	ds_write_b64 v182, v[86:87] offset:16
	v_pk_mul_f32 v[86:87], v[94:95], s[64:65] op_sel_hi:[1,0]
	v_pk_mul_f32 v[88:89], v[96:97], s[64:65] op_sel_hi:[1,0]
	v_cvt_pk_bf16_f32 v86, v86, v87
	v_cvt_pk_bf16_f32 v87, v88, v89
	ds_write_b64 v182, v[86:87] offset:32
	v_pk_mul_f32 v[86:87], v[98:99], s[64:65] op_sel_hi:[1,0]
	v_pk_mul_f32 v[88:89], v[100:101], s[64:65] op_sel_hi:[1,0]
	v_cvt_pk_bf16_f32 v86, v86, v87
	v_cvt_pk_bf16_f32 v87, v88, v89
	ds_write_b64 v182, v[86:87] offset:48
	ds_read_b128 v[186:189], v183
	ds_read_b128 v[190:193], v183 offset:1280
	s_waitcnt lgkmcnt(1)
	global_store_dwordx4 v184, v[186:189], s[70:71]
	s_waitcnt lgkmcnt(0)
	global_store_dwordx4 v184, v[190:193], s[70:71] offset:3072
	v_mov_b64_e32 v[88:89], 0xb152000
	v_mov_b64_e32 v[86:87], 8
	v_mov_b32_e32 v3, v148
	s_and_saveexec_b64 s[0:1], s[6:7]
	v_mov_b64_e32 v[88:89], 0xbd52000
	v_mov_b64_e32 v[86:87], 12
	v_mov_b32_e32 v3, v110
	v_mov_b32_e32 v102, v103
	s_or_b64 exec, exec, s[0:1]
	s_and_b64 s[6:7], s[6:7], s[4:5]
	s_and_saveexec_b64 s[0:1], s[6:7]
	s_cbranch_execz .LBB0_984
	v_readlane_b32 s6, v253, 31
	v_lshlrev_b32_e32 v90, 7, v102
	v_mov_b32_e32 v91, v4
	v_readlane_b32 s7, v253, 32
	v_mov_b32_e32 v1, v4
	s_nop 0
	v_lshl_add_u64 v[92:93], s[6:7], 0, v[90:91]
	v_readlane_b32 s6, v254, 47
	v_readlane_b32 s7, v254, 48
	v_lshl_add_u64 v[98:99], v[92:93], 0, v[0:1]
	s_nop 0
	v_lshl_add_u64 v[90:91], s[6:7], 0, v[90:91]
	v_lshl_add_u64 v[100:101], v[90:91], 0, v[0:1]
	global_load_dwordx4 v[90:93], v[98:99], off
	global_load_dwordx4 v[94:97], v[100:101], off
	global_load_dwordx4 v[194:197], v[98:99], off offset:64
	global_load_dwordx4 v[198:201], v[100:101], off offset:64
	s_waitcnt vmcnt(2)
	v_pk_mul_f32 v[104:105], v[74:75], v[94:95]
	s_nop 0
	v_pk_fma_f32 v[104:105], v[70:71], v[90:91], v[104:105] neg_lo:[0,0,1] neg_hi:[0,0,1]
	v_pk_mul_f32 v[70:71], v[70:71], v[94:95]
	s_nop 0
	v_pk_fma_f32 v[74:75], v[74:75], v[90:91], v[70:71]
	v_pk_mul_f32 v[70:71], v[76:77], v[96:97]
	s_nop 0
	v_pk_fma_f32 v[94:95], v[72:73], v[92:93], v[70:71] neg_lo:[0,0,1] neg_hi:[0,0,1]
	v_pk_mul_f32 v[70:71], v[72:73], v[96:97]
	s_nop 0
	v_pk_fma_f32 v[76:77], v[76:77], v[92:93], v[70:71]
	s_waitcnt vmcnt(0)
	v_pk_mul_f32 v[96:97], v[82:83], v[198:199]
	s_nop 0
	v_pk_fma_f32 v[96:97], v[78:79], v[194:195], v[96:97] neg_lo:[0,0,1] neg_hi:[0,0,1]
	v_pk_mul_f32 v[78:79], v[78:79], v[198:199]
	s_nop 0
	v_pk_fma_f32 v[82:83], v[82:83], v[194:195], v[78:79]
	v_pk_mul_f32 v[70:71], v[84:85], v[200:201]
	v_mov_b32_e32 v78, v96
	v_pk_fma_f32 v[90:91], v[80:81], v[196:197], v[70:71] neg_lo:[0,0,1] neg_hi:[0,0,1]
	v_pk_mul_f32 v[70:71], v[80:81], v[200:201]
	v_mov_b32_e32 v79, v97
	v_pk_fma_f32 v[84:85], v[84:85], v[196:197], v[70:71]
	v_mov_b32_e32 v70, v104
	v_mov_b32_e32 v71, v105
	v_mov_b32_e32 v72, v94
	v_mov_b32_e32 v73, v95
	v_mov_b32_e32 v80, v90
	v_mov_b32_e32 v81, v91
.LBB0_984:
	s_or_b64 exec, exec, s[0:1]
	v_add_u32_e32 v90, v3, v121
	v_ashrrev_i32_e32 v91, 31, v90
	v_lshlrev_b64 v[86:87], v86, v[90:91]
	v_mov_b32_e32 v103, v4
	v_lshl_add_u64 v[88:89], s[26:27], 0, v[88:89]
	v_lshl_add_u64 v[86:87], v[86:87], 0, v[102:103]
	v_mad_u64_u32 v[88:89], s[0:1], v86, s50, v[88:89]
	v_mad_i32_i24 v89, v87, s50, v89
	v_lshl_add_u64 v[86:87], v[118:119], 1, v[88:89]
	v_mov_b32_e32 v3, v4
	v_pk_mul_f32 v[70:71], v[70:71], s[64:65] op_sel_hi:[1,0]
	v_pk_mul_f32 v[72:73], v[72:73], s[64:65] op_sel_hi:[1,0]
	v_lshl_add_u64 v[86:87], v[86:87], 0, v[2:3]
	v_cvt_pk_bf16_f32 v70, v70, v71
	v_cvt_pk_bf16_f32 v71, v72, v73
	s_nop 0
	v_readfirstlane_b32 s70, v86
	v_readfirstlane_b32 s71, v87
	ds_write_b64 v182, v[70:71]
	v_pk_mul_f32 v[70:71], v[74:75], s[64:65] op_sel_hi:[1,0]
	v_pk_mul_f32 v[72:73], v[76:77], s[64:65] op_sel_hi:[1,0]
	v_cvt_pk_bf16_f32 v70, v70, v71
	v_cvt_pk_bf16_f32 v71, v72, v73
	ds_write_b64 v182, v[70:71] offset:16
	v_pk_mul_f32 v[70:71], v[78:79], s[64:65] op_sel_hi:[1,0]
	v_pk_mul_f32 v[72:73], v[80:81], s[64:65] op_sel_hi:[1,0]
	v_cvt_pk_bf16_f32 v70, v70, v71
	v_cvt_pk_bf16_f32 v71, v72, v73
	ds_write_b64 v182, v[70:71] offset:32
	v_pk_mul_f32 v[70:71], v[82:83], s[64:65] op_sel_hi:[1,0]
	v_pk_mul_f32 v[72:73], v[84:85], s[64:65] op_sel_hi:[1,0]
	v_or_b32_e32 v1, 64, v149
	v_cvt_pk_bf16_f32 v70, v70, v71
	v_cvt_pk_bf16_f32 v71, v72, v73
	v_cmp_lt_i32_e64 s[6:7], s89, v1
	s_movk_i32 s0, 0xdf
	v_add_u32_e32 v1, 0xffffe040, v149
	ds_write_b64 v182, v[70:71] offset:48
	ds_read_b128 v[186:189], v183
	ds_read_b128 v[190:193], v183 offset:1280
	s_waitcnt lgkmcnt(1)
	global_store_dwordx4 v184, v[186:189], s[70:71]
	s_waitcnt lgkmcnt(0)
	global_store_dwordx4 v184, v[190:193], s[70:71] offset:3072
	v_bitop3_b32 v70, v149, s0, 64 bitop3:0xc8
	s_movk_i32 s0, 0xfdf
	v_lshrrev_b32_e32 v1, 9, v1
	v_bitop3_b32 v71, v149, s0, 64 bitop3:0xc8
	v_and_b32_e32 v78, 0x7ffff8, v1
	v_mov_b64_e32 v[76:77], 0xb152000
	v_mov_b64_e32 v[72:73], 8
	v_mov_b32_e32 v3, v148
	v_mov_b32_e32 v74, v70
	s_and_saveexec_b64 s[0:1], s[6:7]
	v_mov_b64_e32 v[76:77], 0xbd52000
	v_mov_b64_e32 v[72:73], 12
	v_mov_b32_e32 v3, v78
	v_mov_b32_e32 v74, v71
	s_or_b64 exec, exec, s[0:1]
	s_and_b64 s[14:15], s[6:7], vcc
	s_and_saveexec_b64 s[0:1], s[14:15]
	s_cbranch_execz .LBB0_988
	v_readlane_b32 s14, v253, 31
	v_lshlrev_b32_e32 v80, 7, v74
	v_mov_b32_e32 v81, v4
	v_readlane_b32 s15, v253, 32
	v_mov_b32_e32 v1, v4
	s_nop 0
	v_lshl_add_u64 v[82:83], s[14:15], 0, v[80:81]
	v_readlane_b32 s14, v254, 47
	v_readlane_b32 s15, v254, 48
	v_lshl_add_u64 v[88:89], v[82:83], 0, v[0:1]
	s_nop 0
	v_lshl_add_u64 v[80:81], s[14:15], 0, v[80:81]
	v_lshl_add_u64 v[90:91], v[80:81], 0, v[0:1]
	global_load_dwordx4 v[80:83], v[88:89], off
	global_load_dwordx4 v[84:87], v[90:91], off
	global_load_dwordx4 v[194:197], v[88:89], off offset:64
	global_load_dwordx4 v[198:201], v[90:91], off offset:64
	s_waitcnt vmcnt(2)
	v_pk_mul_f32 v[92:93], v[58:59], v[84:85]
	s_nop 0
	v_pk_fma_f32 v[92:93], v[54:55], v[80:81], v[92:93] neg_lo:[0,0,1] neg_hi:[0,0,1]
	v_pk_mul_f32 v[54:55], v[54:55], v[84:85]
	s_nop 0
	v_pk_fma_f32 v[58:59], v[58:59], v[80:81], v[54:55]
	v_pk_mul_f32 v[54:55], v[60:61], v[86:87]
	s_nop 0
	v_pk_fma_f32 v[84:85], v[56:57], v[82:83], v[54:55] neg_lo:[0,0,1] neg_hi:[0,0,1]
	v_pk_mul_f32 v[54:55], v[56:57], v[86:87]
	s_nop 0
	v_pk_fma_f32 v[60:61], v[60:61], v[82:83], v[54:55]
	s_waitcnt vmcnt(0)
	v_pk_mul_f32 v[86:87], v[66:67], v[198:199]
	s_nop 0
	v_pk_fma_f32 v[86:87], v[62:63], v[194:195], v[86:87] neg_lo:[0,0,1] neg_hi:[0,0,1]
	v_pk_mul_f32 v[62:63], v[62:63], v[198:199]
	s_nop 0
	v_pk_fma_f32 v[66:67], v[66:67], v[194:195], v[62:63]
	v_pk_mul_f32 v[54:55], v[68:69], v[200:201]
	v_mov_b32_e32 v62, v86
	v_pk_fma_f32 v[80:81], v[64:65], v[196:197], v[54:55] neg_lo:[0,0,1] neg_hi:[0,0,1]
	v_pk_mul_f32 v[54:55], v[64:65], v[200:201]
	v_mov_b32_e32 v63, v87
	v_pk_fma_f32 v[68:69], v[68:69], v[196:197], v[54:55]
	v_mov_b32_e32 v54, v92
	v_mov_b32_e32 v55, v93
	v_mov_b32_e32 v56, v84
	v_mov_b32_e32 v57, v85
	v_mov_b32_e32 v64, v80
	v_mov_b32_e32 v65, v81
.LBB0_988:
	s_or_b64 exec, exec, s[0:1]
	v_add_u32_e32 v80, v3, v139
	v_ashrrev_i32_e32 v81, 31, v80
	v_lshlrev_b64 v[72:73], v72, v[80:81]
	v_mov_b32_e32 v75, v4
	v_lshl_add_u64 v[76:77], s[26:27], 0, v[76:77]
	v_lshl_add_u64 v[72:73], v[72:73], 0, v[74:75]
	v_mad_u64_u32 v[74:75], s[0:1], v72, s50, v[76:77]
	v_mad_i32_i24 v75, v73, s50, v75
	v_lshl_add_u64 v[72:73], v[134:135], 1, v[74:75]
	v_mov_b32_e32 v3, v4
	v_pk_mul_f32 v[54:55], v[54:55], s[64:65] op_sel_hi:[1,0]
	v_pk_mul_f32 v[56:57], v[56:57], s[64:65] op_sel_hi:[1,0]
	v_lshl_add_u64 v[72:73], v[72:73], 0, v[2:3]
	v_cvt_pk_bf16_f32 v54, v54, v55
	v_cvt_pk_bf16_f32 v55, v56, v57
	s_nop 0
	v_readfirstlane_b32 s70, v72
	v_readfirstlane_b32 s71, v73
	ds_write_b64 v182, v[54:55]
	v_pk_mul_f32 v[54:55], v[58:59], s[64:65] op_sel_hi:[1,0]
	v_pk_mul_f32 v[56:57], v[60:61], s[64:65] op_sel_hi:[1,0]
	v_cvt_pk_bf16_f32 v54, v54, v55
	v_cvt_pk_bf16_f32 v55, v56, v57
	ds_write_b64 v182, v[54:55] offset:16
	v_pk_mul_f32 v[54:55], v[62:63], s[64:65] op_sel_hi:[1,0]
	v_pk_mul_f32 v[56:57], v[64:65], s[64:65] op_sel_hi:[1,0]
	v_cvt_pk_bf16_f32 v54, v54, v55
	v_cvt_pk_bf16_f32 v55, v56, v57
	ds_write_b64 v182, v[54:55] offset:32
	v_pk_mul_f32 v[54:55], v[66:67], s[64:65] op_sel_hi:[1,0]
	v_pk_mul_f32 v[56:57], v[68:69], s[64:65] op_sel_hi:[1,0]
	v_cvt_pk_bf16_f32 v54, v54, v55
	v_cvt_pk_bf16_f32 v55, v56, v57
	ds_write_b64 v182, v[54:55] offset:48
	ds_read_b128 v[186:189], v183
	ds_read_b128 v[190:193], v183 offset:1280
	s_waitcnt lgkmcnt(1)
	global_store_dwordx4 v184, v[186:189], s[70:71]
	s_waitcnt lgkmcnt(0)
	global_store_dwordx4 v184, v[190:193], s[70:71] offset:3072
	v_mov_b64_e32 v[56:57], 0xb152000
	v_mov_b64_e32 v[54:55], 8
	v_mov_b32_e32 v3, v148
	s_and_saveexec_b64 s[0:1], s[6:7]
	v_mov_b64_e32 v[56:57], 0xbd52000
	v_mov_b64_e32 v[54:55], 12
	v_mov_b32_e32 v3, v78
	v_mov_b32_e32 v70, v71
	s_or_b64 exec, exec, s[0:1]
	s_and_b64 s[6:7], s[6:7], s[4:5]
	s_and_saveexec_b64 s[0:1], s[6:7]
	s_cbranch_execz .LBB0_992
	v_readlane_b32 s6, v253, 31
	v_lshlrev_b32_e32 v58, 7, v70
	v_mov_b32_e32 v59, v4
	v_readlane_b32 s7, v253, 32
	v_mov_b32_e32 v1, v4
	s_nop 0
	v_lshl_add_u64 v[60:61], s[6:7], 0, v[58:59]
	v_readlane_b32 s6, v254, 47
	v_readlane_b32 s7, v254, 48
	v_lshl_add_u64 v[66:67], v[60:61], 0, v[0:1]
	s_nop 0
	v_lshl_add_u64 v[58:59], s[6:7], 0, v[58:59]
	v_lshl_add_u64 v[68:69], v[58:59], 0, v[0:1]
	global_load_dwordx4 v[58:61], v[66:67], off
	global_load_dwordx4 v[62:65], v[68:69], off
	global_load_dwordx4 v[194:197], v[66:67], off offset:64
	global_load_dwordx4 v[198:201], v[68:69], off offset:64
	s_waitcnt vmcnt(2)
	v_pk_mul_f32 v[72:73], v[42:43], v[62:63]
	s_nop 0
	v_pk_fma_f32 v[72:73], v[38:39], v[58:59], v[72:73] neg_lo:[0,0,1] neg_hi:[0,0,1]
	v_pk_mul_f32 v[38:39], v[38:39], v[62:63]
	s_nop 0
	v_pk_fma_f32 v[42:43], v[42:43], v[58:59], v[38:39]
	v_pk_mul_f32 v[38:39], v[44:45], v[64:65]
	s_nop 0
	v_pk_fma_f32 v[62:63], v[40:41], v[60:61], v[38:39] neg_lo:[0,0,1] neg_hi:[0,0,1]
	v_pk_mul_f32 v[38:39], v[40:41], v[64:65]
	s_nop 0
	v_pk_fma_f32 v[44:45], v[44:45], v[60:61], v[38:39]
	s_waitcnt vmcnt(0)
	v_pk_mul_f32 v[64:65], v[50:51], v[198:199]
	s_nop 0
	v_pk_fma_f32 v[64:65], v[46:47], v[194:195], v[64:65] neg_lo:[0,0,1] neg_hi:[0,0,1]
	v_pk_mul_f32 v[46:47], v[46:47], v[198:199]
	s_nop 0
	v_pk_fma_f32 v[50:51], v[50:51], v[194:195], v[46:47]
	v_pk_mul_f32 v[38:39], v[52:53], v[200:201]
	v_mov_b32_e32 v46, v64
	v_pk_fma_f32 v[58:59], v[48:49], v[196:197], v[38:39] neg_lo:[0,0,1] neg_hi:[0,0,1]
	v_pk_mul_f32 v[38:39], v[48:49], v[200:201]
	v_mov_b32_e32 v47, v65
	v_pk_fma_f32 v[52:53], v[52:53], v[196:197], v[38:39]
	v_mov_b32_e32 v38, v72
	v_mov_b32_e32 v39, v73
	v_mov_b32_e32 v40, v62
	v_mov_b32_e32 v41, v63
	v_mov_b32_e32 v48, v58
	v_mov_b32_e32 v49, v59
.LBB0_992:
	s_or_b64 exec, exec, s[0:1]
	v_add_u32_e32 v58, v3, v121
	v_ashrrev_i32_e32 v59, 31, v58
	v_lshlrev_b64 v[54:55], v54, v[58:59]
	v_mov_b32_e32 v71, v4
	v_lshl_add_u64 v[56:57], s[26:27], 0, v[56:57]
	v_lshl_add_u64 v[54:55], v[54:55], 0, v[70:71]
	v_mad_u64_u32 v[56:57], s[0:1], v54, s50, v[56:57]
	v_mad_i32_i24 v57, v55, s50, v57
	v_lshl_add_u64 v[54:55], v[118:119], 1, v[56:57]
	v_mov_b32_e32 v3, v4
	v_pk_mul_f32 v[38:39], v[38:39], s[64:65] op_sel_hi:[1,0]
	v_pk_mul_f32 v[40:41], v[40:41], s[64:65] op_sel_hi:[1,0]
	v_lshl_add_u64 v[54:55], v[54:55], 0, v[2:3]
	v_cvt_pk_bf16_f32 v38, v38, v39
	v_cvt_pk_bf16_f32 v39, v40, v41
	s_nop 0
	v_readfirstlane_b32 s70, v54
	v_readfirstlane_b32 s71, v55
	ds_write_b64 v182, v[38:39]
	v_pk_mul_f32 v[38:39], v[42:43], s[64:65] op_sel_hi:[1,0]
	v_pk_mul_f32 v[40:41], v[44:45], s[64:65] op_sel_hi:[1,0]
	v_cvt_pk_bf16_f32 v38, v38, v39
	v_cvt_pk_bf16_f32 v39, v40, v41
	ds_write_b64 v182, v[38:39] offset:16
	v_pk_mul_f32 v[38:39], v[46:47], s[64:65] op_sel_hi:[1,0]
	v_pk_mul_f32 v[40:41], v[48:49], s[64:65] op_sel_hi:[1,0]
	v_cvt_pk_bf16_f32 v38, v38, v39
	v_cvt_pk_bf16_f32 v39, v40, v41
	ds_write_b64 v182, v[38:39] offset:32
	v_pk_mul_f32 v[38:39], v[50:51], s[64:65] op_sel_hi:[1,0]
	v_pk_mul_f32 v[40:41], v[52:53], s[64:65] op_sel_hi:[1,0]
	v_or_b32_e32 v1, 0x60, v149
	v_cvt_pk_bf16_f32 v38, v38, v39
	v_cvt_pk_bf16_f32 v39, v40, v41
	v_cmp_lt_i32_e64 s[6:7], s89, v1
	s_movk_i32 s0, 0xff
	v_add_u32_e32 v1, 0xffffe060, v149
	ds_write_b64 v182, v[38:39] offset:48
	ds_read_b128 v[186:189], v183
	ds_read_b128 v[190:193], v183 offset:1280
	s_waitcnt lgkmcnt(1)
	global_store_dwordx4 v184, v[186:189], s[70:71]
	s_waitcnt lgkmcnt(0)
	global_store_dwordx4 v184, v[190:193], s[70:71] offset:3072
	v_bitop3_b32 v38, v149, s0, v251 bitop3:0xc8
	s_movk_i32 s0, 0xfff
	v_lshrrev_b32_e32 v1, 9, v1
	v_bitop3_b32 v39, v149, s0, v251 bitop3:0xc8
	v_and_b32_e32 v46, 0x7ffff8, v1
	v_mov_b64_e32 v[44:45], 0xb152000
	v_mov_b64_e32 v[40:41], 8
	v_mov_b32_e32 v3, v148
	v_mov_b32_e32 v42, v38
	s_and_saveexec_b64 s[0:1], s[6:7]
	v_mov_b64_e32 v[44:45], 0xbd52000
	v_mov_b64_e32 v[40:41], 12
	v_mov_b32_e32 v3, v46
	v_mov_b32_e32 v42, v39
	s_or_b64 exec, exec, s[0:1]
	s_and_b64 s[14:15], s[6:7], vcc
	s_and_saveexec_b64 s[0:1], s[14:15]
	s_cbranch_execz .LBB0_996
	v_readlane_b32 s14, v253, 31
	v_lshlrev_b32_e32 v48, 7, v42
	v_mov_b32_e32 v49, v4
	v_readlane_b32 s15, v253, 32
	v_mov_b32_e32 v1, v4
	s_nop 0
	v_lshl_add_u64 v[50:51], s[14:15], 0, v[48:49]
	v_readlane_b32 s14, v254, 47
	v_readlane_b32 s15, v254, 48
	v_lshl_add_u64 v[56:57], v[50:51], 0, v[0:1]
	s_nop 0
	v_lshl_add_u64 v[48:49], s[14:15], 0, v[48:49]
	v_lshl_add_u64 v[58:59], v[48:49], 0, v[0:1]
	global_load_dwordx4 v[48:51], v[56:57], off
	global_load_dwordx4 v[52:55], v[58:59], off
	global_load_dwordx4 v[194:197], v[56:57], off offset:64
	global_load_dwordx4 v[198:201], v[58:59], off offset:64
	s_waitcnt vmcnt(2)
	v_pk_mul_f32 v[60:61], v[26:27], v[52:53]
	s_nop 0
	v_pk_fma_f32 v[60:61], v[22:23], v[48:49], v[60:61] neg_lo:[0,0,1] neg_hi:[0,0,1]
	v_pk_mul_f32 v[22:23], v[22:23], v[52:53]
	s_nop 0
	v_pk_fma_f32 v[26:27], v[26:27], v[48:49], v[22:23]
	v_pk_mul_f32 v[22:23], v[28:29], v[54:55]
	s_nop 0
	v_pk_fma_f32 v[52:53], v[24:25], v[50:51], v[22:23] neg_lo:[0,0,1] neg_hi:[0,0,1]
	v_pk_mul_f32 v[22:23], v[24:25], v[54:55]
	s_nop 0
	v_pk_fma_f32 v[28:29], v[28:29], v[50:51], v[22:23]
	s_waitcnt vmcnt(0)
	v_pk_mul_f32 v[54:55], v[34:35], v[198:199]
	s_nop 0
	v_pk_fma_f32 v[54:55], v[30:31], v[194:195], v[54:55] neg_lo:[0,0,1] neg_hi:[0,0,1]
	v_pk_mul_f32 v[30:31], v[30:31], v[198:199]
	s_nop 0
	v_pk_fma_f32 v[34:35], v[34:35], v[194:195], v[30:31]
	v_pk_mul_f32 v[22:23], v[36:37], v[200:201]
	v_mov_b32_e32 v30, v54
	v_pk_fma_f32 v[48:49], v[32:33], v[196:197], v[22:23] neg_lo:[0,0,1] neg_hi:[0,0,1]
	v_pk_mul_f32 v[22:23], v[32:33], v[200:201]
	v_mov_b32_e32 v31, v55
	v_pk_fma_f32 v[36:37], v[36:37], v[196:197], v[22:23]
	v_mov_b32_e32 v22, v60
	v_mov_b32_e32 v23, v61
	v_mov_b32_e32 v24, v52
	v_mov_b32_e32 v25, v53
	v_mov_b32_e32 v32, v48
	v_mov_b32_e32 v33, v49
.LBB0_996:
	s_or_b64 exec, exec, s[0:1]
	v_add_u32_e32 v48, v3, v139
	v_ashrrev_i32_e32 v49, 31, v48
	v_lshlrev_b64 v[40:41], v40, v[48:49]
	v_mov_b32_e32 v43, v4
	v_lshl_add_u64 v[44:45], s[26:27], 0, v[44:45]
	v_lshl_add_u64 v[40:41], v[40:41], 0, v[42:43]
	v_mad_u64_u32 v[42:43], s[0:1], v40, s50, v[44:45]
	v_mad_i32_i24 v43, v41, s50, v43
	v_lshl_add_u64 v[40:41], v[134:135], 1, v[42:43]
	v_mov_b32_e32 v3, v4
	v_pk_mul_f32 v[22:23], v[22:23], s[64:65] op_sel_hi:[1,0]
	v_pk_mul_f32 v[24:25], v[24:25], s[64:65] op_sel_hi:[1,0]
	v_lshl_add_u64 v[40:41], v[40:41], 0, v[2:3]
	v_cvt_pk_bf16_f32 v22, v22, v23
	v_cvt_pk_bf16_f32 v23, v24, v25
	s_nop 0
	v_readfirstlane_b32 s70, v40
	v_readfirstlane_b32 s71, v41
	ds_write_b64 v182, v[22:23]
	v_pk_mul_f32 v[22:23], v[26:27], s[64:65] op_sel_hi:[1,0]
	v_pk_mul_f32 v[24:25], v[28:29], s[64:65] op_sel_hi:[1,0]
	v_cvt_pk_bf16_f32 v22, v22, v23
	v_cvt_pk_bf16_f32 v23, v24, v25
	ds_write_b64 v182, v[22:23] offset:16
	v_pk_mul_f32 v[22:23], v[30:31], s[64:65] op_sel_hi:[1,0]
	v_pk_mul_f32 v[24:25], v[32:33], s[64:65] op_sel_hi:[1,0]
	v_cvt_pk_bf16_f32 v22, v22, v23
	v_cvt_pk_bf16_f32 v23, v24, v25
	ds_write_b64 v182, v[22:23] offset:32
	v_pk_mul_f32 v[22:23], v[34:35], s[64:65] op_sel_hi:[1,0]
	v_pk_mul_f32 v[24:25], v[36:37], s[64:65] op_sel_hi:[1,0]
	v_cvt_pk_bf16_f32 v22, v22, v23
	v_cvt_pk_bf16_f32 v23, v24, v25
	ds_write_b64 v182, v[22:23] offset:48
	ds_read_b128 v[186:189], v183
	ds_read_b128 v[190:193], v183 offset:1280
	s_waitcnt lgkmcnt(1)
	global_store_dwordx4 v184, v[186:189], s[70:71]
	s_waitcnt lgkmcnt(0)
	global_store_dwordx4 v184, v[190:193], s[70:71] offset:3072
	v_mov_b64_e32 v[24:25], 0xb152000
	v_mov_b64_e32 v[22:23], 8
	s_and_saveexec_b64 s[0:1], s[6:7]
	v_mov_b64_e32 v[24:25], 0xbd52000
	v_mov_b64_e32 v[22:23], 12
	v_mov_b32_e32 v148, v46
	v_mov_b32_e32 v38, v39
	s_or_b64 exec, exec, s[0:1]
	s_and_b64 s[4:5], s[6:7], s[4:5]
	s_and_saveexec_b64 s[0:1], s[4:5]
	s_cbranch_execz .LBB0_915
	v_readlane_b32 s4, v253, 31
	v_lshlrev_b32_e32 v26, 7, v38
	v_mov_b32_e32 v27, v4
	v_readlane_b32 s5, v253, 32
	v_mov_b32_e32 v1, v4
	s_nop 0
	v_lshl_add_u64 v[28:29], s[4:5], 0, v[26:27]
	v_readlane_b32 s4, v254, 47
	v_readlane_b32 s5, v254, 48
	v_lshl_add_u64 v[34:35], v[28:29], 0, v[0:1]
	s_nop 0
	v_lshl_add_u64 v[26:27], s[4:5], 0, v[26:27]
	v_lshl_add_u64 v[0:1], v[26:27], 0, v[0:1]
	global_load_dwordx4 v[26:29], v[34:35], off
	global_load_dwordx4 v[30:33], v[0:1], off
	global_load_dwordx4 v[194:197], v[34:35], off offset:64
	global_load_dwordx4 v[198:201], v[0:1], off offset:64
	s_waitcnt vmcnt(2)
	v_pk_mul_f32 v[36:37], v[10:11], v[30:31]
	s_nop 0
	v_pk_fma_f32 v[36:37], v[6:7], v[26:27], v[36:37] neg_lo:[0,0,1] neg_hi:[0,0,1]
	v_pk_mul_f32 v[6:7], v[6:7], v[30:31]
	s_nop 0
	v_pk_fma_f32 v[10:11], v[10:11], v[26:27], v[6:7]
	v_pk_mul_f32 v[6:7], v[12:13], v[32:33]
	s_nop 0
	v_pk_fma_f32 v[30:31], v[8:9], v[28:29], v[6:7] neg_lo:[0,0,1] neg_hi:[0,0,1]
	v_pk_mul_f32 v[6:7], v[8:9], v[32:33]
	s_nop 0
	v_pk_fma_f32 v[12:13], v[12:13], v[28:29], v[6:7]
	s_waitcnt vmcnt(0)
	v_pk_mul_f32 v[0:1], v[18:19], v[198:199]
	s_nop 0
	v_pk_fma_f32 v[0:1], v[14:15], v[194:195], v[0:1] neg_lo:[0,0,1] neg_hi:[0,0,1]
	v_pk_mul_f32 v[14:15], v[14:15], v[198:199]
	s_nop 0
	v_pk_fma_f32 v[18:19], v[18:19], v[194:195], v[14:15]
	v_pk_mul_f32 v[6:7], v[20:21], v[200:201]
	v_mov_b32_e32 v14, v0
	v_pk_fma_f32 v[26:27], v[16:17], v[196:197], v[6:7] neg_lo:[0,0,1] neg_hi:[0,0,1]
	v_pk_mul_f32 v[6:7], v[16:17], v[200:201]
	v_mov_b32_e32 v15, v1
	v_pk_fma_f32 v[20:21], v[20:21], v[196:197], v[6:7]
	v_mov_b32_e32 v6, v36
	v_mov_b32_e32 v7, v37
	v_mov_b32_e32 v8, v30
	v_mov_b32_e32 v9, v31
	v_mov_b32_e32 v16, v26
	v_mov_b32_e32 v17, v27
	s_branch .LBB0_915
